# attention loop: LDS-DMA issue spread across the QK MFMAs instead of a burst after the barrier
# speedup vs baseline: 1.0024x; 1.0024x over previous
; #define LAS __attribute__((address_space(3)))
; #define PG8_WAIT_V(n) asm volatile("s_waitcnt vmcnt(" #n ")" ::: "memory")
; #define PG8_WAIT_L(n) asm volatile("s_waitcnt lgkmcnt(" #n ")" ::: "memory")
; #define PG8_BAR __builtin_amdgcn_s_barrier()
; #define ATT_STAGE(t, ring) do { const int _so = (int)((size_t)(t) * inc); _Pragma("unroll") for (int _i = 0; _i < 4; ++_i) \
;     __builtin_amdgcn_raw_ptr_buffer_load_lds(srs, (LAS void*)(lds + stg_base + (ring) * 16384 + _i * 1024), 16, (int)soff[_i & 1], _so + (int)(_i * cstride), 0, 0); } while (0)
; DI void attn_item(const Params& p, const int item) {
;     ...
;   for (int t = 0; t < nT - 1; ++t) {
;     PG8_WAIT_L(0); PG8_WAIT_V(4); PG8_BAR;
;     { const int tk = t + 4 < nT ? t + 4 : nT - 1, tv = t + 2 < nT ? t + 2 : nT - 1; if (wid < 4) ATT_STAGE(tk, m1); else ATT_STAGE(tv, m2); }
;     const LAS unsigned char* vb = lds + m0 * 16384;
;     if ((t == tL && tL > 0) || t == tR) {
;       const float f = t == tR ? fR : fL;
; #pragma unroll
;       for (int db = 0; db < 4; ++db)
; #pragma unroll
;         for (int i = 0; i < 16; ++i) O[db][i] *= f;
;     }
.LBB0_987:
	s_mov_b32 s27, s25
	s_mov_b32 s25, s0
	s_and_b64 s[0:1], s[8:9], exec
	s_cselect_b32 s0, s27, s25
	s_add_i32 s1, s4, s28
	s_lshl_b32 s0, s0, 14
	s_min_u32 s1, s1, s20
	s_add_i32 s98, s18, s0
	s_waitcnt lgkmcnt(0)
	s_mul_i32 s99, s1, s17
	s_waitcnt vmcnt(4)
	s_barrier
	s_cmp_eq_u32 s19, s28
	s_cselect_b64 s[0:1], -1, 0
	s_and_b64 s[30:31], s[10:11], s[0:1]
	s_cmp_eq_u32 s5, s24
	s_cselect_b64 s[0:1], -1, 0
	s_or_b64 s[30:31], s[30:31], s[0:1]
	s_andn2_b64 vcc, exec, s[30:31]
	s_cbranch_vccnz .LBB0_989
	v_cndmask_b32_e64 v64, v229, v230, s[0:1]
	v_pk_mul_f32 v[62:63], v[62:63], v[64:65] op_sel_hi:[1,0]
	v_pk_mul_f32 v[60:61], v[60:61], v[64:65] op_sel_hi:[1,0]
	v_pk_mul_f32 v[58:59], v[58:59], v[64:65] op_sel_hi:[1,0]
	v_pk_mul_f32 v[56:57], v[56:57], v[64:65] op_sel_hi:[1,0]
	v_pk_mul_f32 v[54:55], v[54:55], v[64:65] op_sel_hi:[1,0]
	v_pk_mul_f32 v[52:53], v[52:53], v[64:65] op_sel_hi:[1,0]
	v_pk_mul_f32 v[50:51], v[50:51], v[64:65] op_sel_hi:[1,0]
	v_pk_mul_f32 v[48:49], v[48:49], v[64:65] op_sel_hi:[1,0]
	v_pk_mul_f32 v[46:47], v[46:47], v[64:65] op_sel_hi:[1,0]
	v_pk_mul_f32 v[44:45], v[44:45], v[64:65] op_sel_hi:[1,0]
	v_pk_mul_f32 v[42:43], v[42:43], v[64:65] op_sel_hi:[1,0]
	v_pk_mul_f32 v[40:41], v[40:41], v[64:65] op_sel_hi:[1,0]
	v_pk_mul_f32 v[38:39], v[38:39], v[64:65] op_sel_hi:[1,0]
	v_pk_mul_f32 v[36:37], v[36:37], v[64:65] op_sel_hi:[1,0]
	v_pk_mul_f32 v[34:35], v[34:35], v[64:65] op_sel_hi:[1,0]
	v_pk_mul_f32 v[32:33], v[32:33], v[64:65] op_sel_hi:[1,0]
	v_pk_mul_f32 v[30:31], v[30:31], v[64:65] op_sel_hi:[1,0]
	v_pk_mul_f32 v[28:29], v[28:29], v[64:65] op_sel_hi:[1,0]
	v_pk_mul_f32 v[26:27], v[26:27], v[64:65] op_sel_hi:[1,0]
	v_pk_mul_f32 v[24:25], v[24:25], v[64:65] op_sel_hi:[1,0]
	v_pk_mul_f32 v[22:23], v[22:23], v[64:65] op_sel_hi:[1,0]
	v_pk_mul_f32 v[20:21], v[20:21], v[64:65] op_sel_hi:[1,0]
	v_pk_mul_f32 v[18:19], v[18:19], v[64:65] op_sel_hi:[1,0]
	v_pk_mul_f32 v[16:17], v[16:17], v[64:65] op_sel_hi:[1,0]
	v_pk_mul_f32 v[14:15], v[14:15], v[64:65] op_sel_hi:[1,0]
	v_pk_mul_f32 v[12:13], v[12:13], v[64:65] op_sel_hi:[1,0]
	v_pk_mul_f32 v[10:11], v[10:11], v[64:65] op_sel_hi:[1,0]
	v_pk_mul_f32 v[8:9], v[8:9], v[64:65] op_sel_hi:[1,0]
	v_pk_mul_f32 v[6:7], v[6:7], v[64:65] op_sel_hi:[1,0]
	v_pk_mul_f32 v[4:5], v[4:5], v[64:65] op_sel_hi:[1,0]
	v_pk_mul_f32 v[2:3], v[2:3], v[64:65] op_sel_hi:[1,0]
	v_pk_mul_f32 v[0:1], v[0:1], v[64:65] op_sel_hi:[1,0]

; #define LAS __attribute__((address_space(3)))
; #define PG8_SCHED __builtin_amdgcn_sched_barrier(0)
; #define MFMA32(a, b, c) __builtin_amdgcn_mfma_f32_32x32x16_bf16((a), (b), (c), 0, 0, 0)
; #define ATT_LDK(ring) do { _Pragma("unroll") for (int kh = 0; kh < 2; ++kh) _Pragma("unroll") for (int ks = 0; ks < 4; ++ks) \
;     kf[kh][ks] = *(const LAS bf16x8*)(lds + (ring) * 16384 + kh * 4096 + koff[ks]); } while (0)
; DI void attn_item(const Params& p, const int item) {
;     ...
;     ATT_QK(t + 1);
;     PG8_SCHED;
; #pragma unroll
;     for (int db = 0; db < 4; ++db)
; #pragma unroll
;       for (int s = 0; s < 2; ++s) vfB[db][s] = *(const LAS bf16x8*)(vb + db * 4096 + voff[s + 2]);
;     bf16x8 pfN[4];
; #pragma unroll
;     for (int s = 0; s < 2; ++s)
; #pragma unroll
;       for (int db = 0; db < 4; ++db) O[db] = MFMA32(vfA[db][s], pf[s], O[db]);
;     ATT_SM(0, pfN);
;     PG8_SCHED;
;     ATT_LDK(m2);
; #pragma unroll
;     for (int s = 0; s < 2; ++s)
; #pragma unroll
;       for (int db = 0; db < 4; ++db) O[db] = MFMA32(vfB[db][s], pf[s + 2], O[db]);
;     ATT_SM(1, pfN);
;     PG8_SCHED;
; #pragma unroll
;     for (int s = 0; s < 4; ++s) pf[s] = pfN[s];
;     { const int mm = m0; m0 = m1; m1 = m2; m2 = mm; }
.LBB0_993:
	s_mov_b32 m0, s98
	s_waitcnt lgkmcnt(10)
	buffer_load_dwordx4 v218, s[64:67], s99 offen lds
	v_mfma_f32_32x32x16_bf16 v[64:79], v[148:151], v[100:103], v[64:79]
	s_cmp_eq_u32 s23, s28
	s_cselect_b64 vcc, -1, 0
	s_cmp_eq_u32 s22, s24
	s_cselect_b64 s[100:101], -1, 0
	v_mfma_f32_32x32x16_bf16 v[80:95], v[144:147], v[100:103], v[80:95]
	s_add_i32 m0, s98, 0x400
	s_add_i32 s99, s99, s7
	buffer_load_dwordx4 v219, s[64:67], s99 offen lds
	v_mfma_f32_32x32x16_bf16 v[64:79], v[140:143], v[104:107], v[64:79]
	v_mfma_f32_32x32x16_bf16 v[80:95], v[136:139], v[104:107], v[80:95]
	s_add_i32 m0, s98, 0x800
	s_add_i32 s99, s99, s7
	buffer_load_dwordx4 v218, s[64:67], s99 offen lds
	s_waitcnt lgkmcnt(9)
	v_mfma_f32_32x32x16_bf16 v[64:79], v[132:135], v[108:111], v[64:79]
	v_mul_f32_e32 v132, v229, v231
	v_cndmask_b32_e32 v132, v231, v132, vcc
	v_mul_f32_e32 v133, v230, v132
	v_cndmask_b32_e64 v144, v132, v133, s[100:101]
	s_waitcnt lgkmcnt(8)
	v_mfma_f32_32x32x16_bf16 v[80:95], v[128:131], v[108:111], v[80:95]
	s_add_i32 m0, s98, 0xc00
	s_add_i32 s99, s99, s7
	buffer_load_dwordx4 v219, s[64:67], s99 offen lds
	s_waitcnt lgkmcnt(7)
	v_mfma_f32_32x32x16_bf16 v[48:63], v[176:179], v[120:123], v[48:63]
	s_nop 2
	v_exp_f32_e32 v64, v64
	v_exp_f32_e32 v65, v65
	v_exp_f32_e32 v66, v66
	v_add_u32_e32 v140, s30, v226
	v_exp_f32_e32 v67, v67
	v_exp_f32_e32 v68, v68
	v_exp_f32_e32 v69, v69
	s_waitcnt lgkmcnt(6)
	v_mfma_f32_32x32x16_bf16 v[32:47], v[180:183], v[120:123], v[32:47]
	v_exp_f32_e32 v70, v70
	v_exp_f32_e32 v71, v71
	v_exp_f32_e32 v72, v72
	v_exp_f32_e32 v73, v73
	v_exp_f32_e32 v74, v74
	v_exp_f32_e32 v75, v75
	v_exp_f32_e32 v76, v76
	s_waitcnt lgkmcnt(3)
	v_mfma_f32_32x32x16_bf16 v[16:31], v[184:187], v[120:123], v[16:31]
	v_exp_f32_e32 v77, v77
	v_exp_f32_e32 v78, v78
	v_exp_f32_e32 v79, v79
	s_waitcnt lgkmcnt(2)
	v_mfma_f32_32x32x16_bf16 v[0:15], v[188:191], v[120:123], v[0:15]
	v_add_u32_e32 v120, s30, v225
	ds_read_b128 v[128:131], v140 offset:49152
	ds_read_b128 v[132:135], v140 offset:53248
	ds_read_b128 v[176:179], v120 offset:49152
	ds_read_b128 v[180:183], v120 offset:53248
	ds_read_b128 v[136:139], v140 offset:57344
	ds_read_b128 v[140:143], v140 offset:61440
	v_cvt_pk_bf16_f32 v121, v66, v67
	v_cvt_pk_bf16_f32 v122, v68, v69
	v_cvt_pk_bf16_f32 v123, v70, v71
	v_mfma_f32_32x32x16_bf16 v[48:63], v[172:175], v[112:115], v[48:63]
	ds_read_b128 v[172:175], v120 offset:57344
	ds_read_b128 v[184:187], v120 offset:61440
	v_cvt_pk_bf16_f32 v120, v64, v65
	v_add_f32_e32 v64, v144, v64
	v_add_f32_e32 v64, v65, v64
	v_add_f32_e32 v64, v66, v64
	v_add_f32_e32 v64, v67, v64
	v_add_f32_e32 v64, v68, v64
	v_add_f32_e32 v64, v69, v64
	v_mfma_f32_32x32x16_bf16 v[32:47], v[168:171], v[112:115], v[32:47]
	v_add_f32_e32 v64, v70, v64
	v_add_f32_e32 v64, v71, v64
	v_add_f32_e32 v64, v72, v64
	v_add_f32_e32 v64, v73, v64
	v_add_f32_e32 v64, v74, v64
	v_add_f32_e32 v64, v75, v64
	v_add_f32_e32 v64, v76, v64
	s_waitcnt lgkmcnt(9)
	v_mfma_f32_32x32x16_bf16 v[16:31], v[164:167], v[112:115], v[16:31]
	v_add_f32_e32 v64, v77, v64
	v_add_f32_e32 v64, v78, v64
	s_waitcnt lgkmcnt(8)
	v_mfma_f32_32x32x16_bf16 v[0:15], v[160:163], v[112:115], v[0:15]
	v_cvt_pk_bf16_f32 v112, v72, v73
	v_cvt_pk_bf16_f32 v113, v74, v75
	v_cvt_pk_bf16_f32 v114, v76, v77
	v_cvt_pk_bf16_f32 v115, v78, v79
	s_lshl_b32 s0, s25, 14
	s_add_i32 s0, s0, 0
	v_add_u32_e32 v65, s0, v220
	s_waitcnt lgkmcnt(7)
	v_mfma_f32_32x32x16_bf16 v[48:63], v[128:131], v[124:127], v[48:63]
	v_add_u32_e32 v66, s0, v221
	v_add_u32_e32 v67, s0, v222
	v_add_u32_e32 v68, s0, v223
	v_add_f32_e32 v64, v79, v64
	v_exp_f32_e32 v69, v84
	v_exp_f32_e32 v70, v85
	v_exp_f32_e32 v71, v86
	s_waitcnt lgkmcnt(6)
	v_mfma_f32_32x32x16_bf16 v[32:47], v[132:135], v[124:127], v[32:47]
	v_exp_f32_e32 v72, v87
	v_exp_f32_e32 v73, v88
	v_exp_f32_e32 v74, v89
	v_exp_f32_e32 v75, v90
	v_exp_f32_e32 v76, v91
	v_exp_f32_e32 v77, v92
	v_exp_f32_e32 v78, v93
	s_waitcnt lgkmcnt(3)
	v_mfma_f32_32x32x16_bf16 v[16:31], v[136:139], v[124:127], v[16:31]
	v_exp_f32_e32 v79, v94
	s_waitcnt lgkmcnt(2)
	v_mfma_f32_32x32x16_bf16 v[0:15], v[140:143], v[124:127], v[0:15]
	ds_read_b128 v[152:155], v65
	ds_read_b128 v[156:159], v65 offset:4096
	ds_read_b128 v[148:151], v66
	ds_read_b128 v[144:147], v66 offset:4096
	ds_read_b128 v[140:143], v67
	ds_read_b128 v[136:139], v67 offset:4096
	ds_read_b128 v[132:135], v68
	ds_read_b128 v[128:131], v68 offset:4096
	v_exp_f32_e32 v65, v80
	v_exp_f32_e32 v66, v81
	v_exp_f32_e32 v67, v82
	v_exp_f32_e32 v68, v83
	v_add_f32_e32 v64, v65, v64
	v_add_f32_e32 v64, v66, v64
	v_add_f32_e32 v64, v67, v64
	v_add_f32_e32 v64, v68, v64
	v_add_f32_e32 v64, v69, v64
	v_add_f32_e32 v64, v70, v64
	v_mfma_f32_32x32x16_bf16 v[48:63], v[176:179], v[116:119], v[48:63]
	v_add_f32_e32 v64, v71, v64
	v_add_f32_e32 v64, v72, v64
	v_add_f32_e32 v64, v73, v64
	v_exp_f32_e32 v80, v95
	v_add_f32_e32 v64, v74, v64
	v_add_f32_e32 v64, v75, v64
	v_add_f32_e32 v64, v76, v64
	v_mfma_f32_32x32x16_bf16 v[32:47], v[180:183], v[116:119], v[32:47]
	v_add_f32_e32 v64, v77, v64
	v_cvt_pk_bf16_f32 v124, v65, v66
	v_cvt_pk_bf16_f32 v125, v67, v68
	v_cvt_pk_bf16_f32 v126, v69, v70
	v_cvt_pk_bf16_f32 v127, v71, v72
	v_add_f32_e32 v64, v78, v64
	v_add_f32_e32 v64, v79, v64
	s_waitcnt lgkmcnt(9)
	v_mfma_f32_32x32x16_bf16 v[16:31], v[172:175], v[116:119], v[16:31]
	s_waitcnt lgkmcnt(8)
	v_mfma_f32_32x32x16_bf16 v[0:15], v[184:187], v[116:119], v[0:15]
	v_cvt_pk_bf16_f32 v116, v73, v74
	v_cvt_pk_bf16_f32 v117, v75, v76
	v_cvt_pk_bf16_f32 v118, v77, v78
	v_cvt_pk_bf16_f32 v119, v79, v80
	s_add_i32 s24, s24, 64
	s_cmp_eq_u32 s20, s29
	v_add_f32_e32 v231, v80, v64
	s_cbranch_scc1 .LBB0_995
	s_mov_b32 s28, s29
	s_mov_b32 s0, s26
	s_mov_b32 s26, s27
	s_branch .LBB0_987

; __global__ void __launch_bounds__(512, 2) mega(Params p) {
	.amdhsa_kernel _Z4mega6Params
		.amdhsa_group_segment_fixed_size 0
		.amdhsa_private_segment_fixed_size 0
		.amdhsa_kernarg_size 392
		.amdhsa_user_sgpr_count 2
		.amdhsa_user_sgpr_dispatch_ptr 0
		.amdhsa_user_sgpr_queue_ptr 0
		.amdhsa_user_sgpr_kernarg_segment_ptr 1
		.amdhsa_user_sgpr_dispatch_id 0
		.amdhsa_user_sgpr_kernarg_preload_length 0
		.amdhsa_user_sgpr_kernarg_preload_offset 0
		.amdhsa_user_sgpr_private_segment_size 0
		.amdhsa_uses_dynamic_stack 0
		.amdhsa_enable_private_segment 0
		.amdhsa_system_sgpr_workgroup_id_x 1
		.amdhsa_system_sgpr_workgroup_id_y 0
		.amdhsa_system_sgpr_workgroup_id_z 0
		.amdhsa_system_sgpr_workgroup_info 0
		.amdhsa_system_vgpr_workitem_id 2
		.amdhsa_next_free_vgpr 237
		.amdhsa_next_free_sgpr 102
		.amdhsa_accum_offset 240
		.amdhsa_reserve_vcc 1
		.amdhsa_float_round_mode_32 0
		.amdhsa_float_round_mode_16_64 0
		.amdhsa_float_denorm_mode_32 3
		.amdhsa_float_denorm_mode_16_64 3
		.amdhsa_dx10_clamp 1
		.amdhsa_ieee_mode 1
		.amdhsa_fp16_overflow 0
		.amdhsa_tg_split 0
		.amdhsa_exception_fp_ieee_invalid_op 0
		.amdhsa_exception_fp_denorm_src 0
		.amdhsa_exception_fp_ieee_div_zero 0
		.amdhsa_exception_fp_ieee_overflow 0
		.amdhsa_exception_fp_ieee_underflow 0
		.amdhsa_exception_fp_ieee_inexact 0
		.amdhsa_exception_int_div_zero 0
	.end_amdhsa_kernel

; __global__ void __launch_bounds__(512, 2) mega(Params p) {
amdhsa.kernels:
  - .agpr_count:     0
    .args:
      - .offset:         0
        .size:           136
        .value_kind:     by_value
      - .offset:         136
        .size:           4
        .value_kind:     hidden_block_count_x
      - .offset:         140
        .size:           4
        .value_kind:     hidden_block_count_y
      - .offset:         144
        .size:           4
        .value_kind:     hidden_block_count_z
      - .offset:         148
        .size:           2
        .value_kind:     hidden_group_size_x
      - .offset:         150
        .size:           2
        .value_kind:     hidden_group_size_y
      - .offset:         152
        .size:           2
        .value_kind:     hidden_group_size_z
      - .offset:         154
        .size:           2
        .value_kind:     hidden_remainder_x
      - .offset:         156
        .size:           2
        .value_kind:     hidden_remainder_y
      - .offset:         158
        .size:           2
        .value_kind:     hidden_remainder_z
      - .offset:         176
        .size:           8
        .value_kind:     hidden_global_offset_x
      - .offset:         184
        .size:           8
        .value_kind:     hidden_global_offset_y
      - .offset:         192
        .size:           8
        .value_kind:     hidden_global_offset_z
      - .offset:         200
        .size:           2
        .value_kind:     hidden_grid_dims
      - .offset:         224
        .size:           8
        .value_kind:     hidden_multigrid_sync_arg
      - .offset:         256
        .size:           4
        .value_kind:     hidden_dynamic_lds_size
    .group_segment_fixed_size: 0
    .kernarg_segment_align: 8
    .kernarg_segment_size: 392
    .language:       OpenCL C
    .language_version:
      - 2
      - 0
    .max_flat_workgroup_size: 512
    .name:           _Z4mega6Params
    .private_segment_fixed_size: 0
    .sgpr_count:     108
    .sgpr_spill_count: 20
    .symbol:         _Z4mega6Params.kd
    .uniform_work_group_size: 1
    .uses_dynamic_stack: false
    .vgpr_count:     237
    .vgpr_spill_count: 0
    .wavefront_size: 64
